# hand-written software-pipelined rmsnorm+modulate loops (3 bf16 sites): next-row prefetch, DPP wave reduce, hoisted g loads
# speedup vs baseline: 1.0083x; 1.0083x over previous
; DI unsigned cvt_pk_bf16(float lo, float hi) { unsigned r; asm volatile("v_cvt_pk_bf16_f32 %0, %1, %2" : "=v"(r) : "v"(lo), "v"(hi)); return r; }
; DI float bflo(unsigned w) { return __uint_as_float(w << 16); }
; DI float bfhi(unsigned w) { return __uint_as_float(w & 0xffff0000u); }
; template <bool XI32>
; DI void phase_mod(const Frame& F, const void* xP, const void* xS, const float* g, const float* mods_l, int sidx, bool pool_out) {
;     ...
;     for (int row = F.gw; row < NT; row += F.NGW) {
;         const int seq = seq_of_row(row);
;         f32x4 v[4]; float ss = 0.f;
;         if constexpr (XI32) { const float* xr = (const float*)(row < NP ? xP : xS) + (size_t)row * DM + 4 * F.lane;
; #pragma unroll
;             for (int j = 0; j < 4; ++j) v[j] = *(const f32x4*)(xr + 256 * j);
;         } else { const bf16_t* xr = (const bf16_t*)xP + (size_t)row * DM + 4 * F.lane;
; #pragma unroll
;             for (int j = 0; j < 4; ++j) { const u32x2 q = *(const u32x2*)(xr + 256 * j); v[j] = (f32x4){bflo(q.x), bfhi(q.x), bflo(q.y), bfhi(q.y)}; } }
; #pragma unroll
;         for (int j = 0; j < 4; ++j) ss += (v[j][0] * v[j][0] + v[j][1] * v[j][1]) + (v[j][2] * v[j][2] + v[j][3] * v[j][3]);
;         const float rstd = 1.f / sqrtf(wave_sum(ss) * (1.f / DM) + EPS);
;         const float* sh = mods_l + (size_t)seq * MODW + sidx * DM; const float* sc = sh + DM;
;         const int pos = pos_of_row(row); const int tl = row < NP ? SEQ : DSEQ;
;         float* po = nullptr;
;         if (pool_out && pos >= tl - 15) po = row < NP ? F.out + O_PP + ((size_t)seq * 15 + (pos - (tl - 15))) * DM : F.out + O_PS + ((size_t)(seq - 2) * 15 + (pos - (tl - 15))) * DM;
;         f32x4 g4v[4], s4v[4], c4v[4];
; #pragma unroll
;         for (int j = 0; j < 4; ++j) { const int col = 4 * F.lane + 256 * j; g4v[j] = *(const f32x4*)(g + col); s4v[j] = *(const f32x4*)(sh + col); c4v[j] = *(const f32x4*)(sc + col); }
; #pragma unroll
;         for (int j = 0; j < 4; ++j) { const int col = 4 * F.lane + 256 * j;
;             const f32x4 g4 = g4v[j], s4 = s4v[j], c4 = c4v[j];
;             const f32x4 y = (v[j] * rstd) * g4 * (1.f + c4) + s4;
;             u32x2 w; w.x = cvt_pk_bf16(y[0], y[1]); w.y = cvt_pk_bf16(y[2], y[3]);
;             *(u32x2*)(U + (size_t)row * DM + col) = w;
;             if (po) *(f32x4*)(po + col) = y; }
;     }
.LBB0_69:
	s_ashr_i32 s0, s0, 6
	v_readlane_b32 s1, v253, 2
	s_add_i32 s20, s0, s1
	s_cmp_lg_u32 s15, 0
	v_writelane_b32 v255, s15, 24
	s_cselect_b64 s[0:1], -1, 0
	v_writelane_b32 v255, s0, 25
	v_and_b32_e32 v1, 63, v1
	s_and_b64 vcc, exec, s[0:1]
	v_writelane_b32 v255, s1, 26
	s_mov_b64 s[0:1], -1
	s_cbranch_vccz .LBB0_74
	v_and_b32_e32 v2, 63, v220
	v_mov_b32_e32 v5, 0x23110
	v_mov_b32_e32 v6, 0x23058
	ds_read_b64 v[8:9], v5
	ds_read_b64 v[10:11], v6
	v_lshlrev_b32_e32 v3, 4, v2
	v_lshlrev_b32_e32 v2, 3, v2
	v_add_u32_e32 v4, 0x1000, v3
	v_readlane_b32 s45, v255, 24
	v_readlane_b32 s25, v253, 2
	v_readfirstlane_b32 s15, v220
	s_lshr_b32 s15, s15, 6
	s_add_i32 s15, s15, s25
	s_waitcnt lgkmcnt(0)
	v_readfirstlane_b32 s42, v8
	v_readfirstlane_b32 s43, v9
	v_readfirstlane_b32 s78, v10
	v_readfirstlane_b32 s79, v11
	s_mul_i32 s25, s45, 0x3000
	s_add_i32 s25, s25, 0
	s_add_u32 s78, s78, s25
	s_addc_u32 s79, s79, 0
	global_load_dwordx4 v[140:143], v3, s[78:79]
	global_load_dwordx4 v[144:147], v3, s[78:79] offset:1024
	global_load_dwordx4 v[148:151], v3, s[78:79] offset:2048
	global_load_dwordx4 v[152:155], v3, s[78:79] offset:3072
	s_mul_i32 s25, s45, 0x5a000
	s_add_i32 s25, s25, 1048576
	s_add_u32 s48, s42, s25
	s_addc_u32 s49, s43, 0
	s_lshl_b32 s25, s15, 11
	s_add_i32 s25, s25, 0xa400000
	s_add_u32 s92, s42, s25
	s_addc_u32 s93, s43, 0
	global_load_dwordx2 v[196:197], v2, s[92:93]
	global_load_dwordx2 v[198:199], v2, s[92:93] offset:512
	global_load_dwordx2 v[200:201], v2, s[92:93] offset:1024
	global_load_dwordx2 v[202:203], v2, s[92:93] offset:1536
.Lpm_a_loop:
	s_lshr_b32 s25, s15, 13
	s_sub_i32 s32, s15, 0x4000
	s_lshr_b32 s32, s32, 5
	s_add_i32 s32, s32, 2
	s_cmp_lt_i32 s15, 0x4000
	s_cselect_b32 s25, s25, s32
	s_mul_i32 s32, s25, 0x9000
	s_add_u32 s78, s48, s32
	s_addc_u32 s79, s49, 0
	global_load_dwordx4 v[156:159], v3, s[78:79]
	global_load_dwordx4 v[160:163], v3, s[78:79] offset:1024
	global_load_dwordx4 v[164:167], v3, s[78:79] offset:2048
	global_load_dwordx4 v[168:171], v3, s[78:79] offset:3072
	global_load_dwordx4 v[180:183], v4, s[78:79]
	global_load_dwordx4 v[184:187], v4, s[78:79] offset:1024
	global_load_dwordx4 v[188:191], v4, s[78:79] offset:2048
	global_load_dwordx4 v[192:195], v4, s[78:79] offset:3072
	s_lshl_b32 s32, s15, 11
	s_add_i32 s32, s32, 0xe500000
	s_add_u32 s98, s42, s32
	s_addc_u32 s99, s43, 0
	s_add_i32 s41, s15, s94
	s_lshl_b32 s32, s41, 11
	s_add_i32 s32, s32, 0xa400000
	s_add_u32 s92, s42, s32
	s_addc_u32 s93, s43, 0
	s_waitcnt vmcnt(8)
	v_lshlrev_b32_e32 v30, 16, v196
	v_and_b32_e32 v31, 0xffff0000, v196
	v_lshlrev_b32_e32 v32, 16, v197
	v_and_b32_e32 v33, 0xffff0000, v197
	v_lshlrev_b32_e32 v34, 16, v198
	v_and_b32_e32 v35, 0xffff0000, v198
	v_lshlrev_b32_e32 v36, 16, v199
	v_and_b32_e32 v37, 0xffff0000, v199
	v_lshlrev_b32_e32 v38, 16, v200
	v_and_b32_e32 v39, 0xffff0000, v200
	v_lshlrev_b32_e32 v40, 16, v201
	v_and_b32_e32 v41, 0xffff0000, v201
	v_lshlrev_b32_e32 v42, 16, v202
	v_and_b32_e32 v43, 0xffff0000, v202
	v_lshlrev_b32_e32 v44, 16, v203
	v_and_b32_e32 v45, 0xffff0000, v203
	global_load_dwordx2 v[196:197], v2, s[92:93]
	global_load_dwordx2 v[198:199], v2, s[92:93] offset:512
	global_load_dwordx2 v[200:201], v2, s[92:93] offset:1024
	global_load_dwordx2 v[202:203], v2, s[92:93] offset:1536
	v_mul_f32_e32 v5, v30, v30
	v_mul_f32_e32 v6, v31, v31
	v_mul_f32_e32 v7, v32, v32
	v_mul_f32_e32 v8, v33, v33
	v_fmac_f32_e32 v5, v34, v34
	v_fmac_f32_e32 v6, v35, v35
	v_fmac_f32_e32 v7, v36, v36
	v_fmac_f32_e32 v8, v37, v37
	v_fmac_f32_e32 v5, v38, v38
	v_fmac_f32_e32 v6, v39, v39
	v_fmac_f32_e32 v7, v40, v40
	v_fmac_f32_e32 v8, v41, v41
	v_fmac_f32_e32 v5, v42, v42
	v_fmac_f32_e32 v6, v43, v43
	v_fmac_f32_e32 v7, v44, v44
	v_fmac_f32_e32 v8, v45, v45
	v_add_f32_e32 v5, v5, v6
	v_add_f32_e32 v7, v7, v8
	v_add_f32_e32 v5, v5, v7
	s_nop 1
	v_add_f32_dpp v5, v5, v5 quad_perm:[1,0,3,2] row_mask:0xf bank_mask:0xf
	s_nop 1
	v_add_f32_dpp v5, v5, v5 quad_perm:[2,3,0,1] row_mask:0xf bank_mask:0xf
	s_nop 1
	v_add_f32_dpp v5, v5, v5 row_half_mirror row_mask:0xf bank_mask:0xf
	s_nop 1
	v_add_f32_dpp v5, v5, v5 row_mirror row_mask:0xf bank_mask:0xf
	s_nop 1
	v_readlane_b32 s25, v5, 0
	v_readlane_b32 s32, v5, 16
	v_readlane_b32 s66, v5, 32
	v_readlane_b32 s69, v5, 48
	v_mov_b32_e32 v7, 0x358637bd
	v_mov_b32_e32 v6, s25
	v_add_f32_e32 v6, s32, v6
	v_add_f32_e32 v6, s66, v6
	v_add_f32_e32 v6, s69, v6
	v_fmamk_f32 v6, v6, 0x3a800000, v7
	v_rsq_f32_e32 v58, v6
	s_waitcnt vmcnt(4)
	v_pk_add_f32 v[180:181], v[180:181], 1.0 op_sel_hi:[1,0]
	v_pk_add_f32 v[182:183], v[182:183], 1.0 op_sel_hi:[1,0]
	v_pk_add_f32 v[184:185], v[184:185], 1.0 op_sel_hi:[1,0]
	v_pk_add_f32 v[186:187], v[186:187], 1.0 op_sel_hi:[1,0]
	v_pk_add_f32 v[188:189], v[188:189], 1.0 op_sel_hi:[1,0]
	v_pk_add_f32 v[190:191], v[190:191], 1.0 op_sel_hi:[1,0]
	v_pk_add_f32 v[192:193], v[192:193], 1.0 op_sel_hi:[1,0]
	v_pk_add_f32 v[194:195], v[194:195], 1.0 op_sel_hi:[1,0]
	v_pk_mul_f32 v[30:31], v[58:59], v[30:31] op_sel_hi:[0,1]
	v_pk_mul_f32 v[32:33], v[58:59], v[32:33] op_sel_hi:[0,1]
	v_pk_mul_f32 v[34:35], v[58:59], v[34:35] op_sel_hi:[0,1]
	v_pk_mul_f32 v[36:37], v[58:59], v[36:37] op_sel_hi:[0,1]
	v_pk_mul_f32 v[38:39], v[58:59], v[38:39] op_sel_hi:[0,1]
	v_pk_mul_f32 v[40:41], v[58:59], v[40:41] op_sel_hi:[0,1]
	v_pk_mul_f32 v[42:43], v[58:59], v[42:43] op_sel_hi:[0,1]
	v_pk_mul_f32 v[44:45], v[58:59], v[44:45] op_sel_hi:[0,1]
	v_pk_mul_f32 v[30:31], v[30:31], v[140:141]
	v_pk_mul_f32 v[32:33], v[32:33], v[142:143]
	v_pk_mul_f32 v[34:35], v[34:35], v[144:145]
	v_pk_mul_f32 v[36:37], v[36:37], v[146:147]
	v_pk_mul_f32 v[38:39], v[38:39], v[148:149]
	v_pk_mul_f32 v[40:41], v[40:41], v[150:151]
	v_pk_mul_f32 v[42:43], v[42:43], v[152:153]
	v_pk_mul_f32 v[44:45], v[44:45], v[154:155]
	v_pk_fma_f32 v[30:31], v[30:31], v[180:181], v[156:157]
	v_pk_fma_f32 v[32:33], v[32:33], v[182:183], v[158:159]
	v_pk_fma_f32 v[34:35], v[34:35], v[184:185], v[160:161]
	v_pk_fma_f32 v[36:37], v[36:37], v[186:187], v[162:163]
	v_pk_fma_f32 v[38:39], v[38:39], v[188:189], v[164:165]
	v_pk_fma_f32 v[40:41], v[40:41], v[190:191], v[166:167]
	v_pk_fma_f32 v[42:43], v[42:43], v[192:193], v[168:169]
	v_pk_fma_f32 v[44:45], v[44:45], v[194:195], v[170:171]
	v_cvt_pk_bf16_f32 v46, v30, v31
	v_cvt_pk_bf16_f32 v47, v32, v33
	v_cvt_pk_bf16_f32 v48, v34, v35
	v_cvt_pk_bf16_f32 v49, v36, v37
	v_cvt_pk_bf16_f32 v50, v38, v39
	v_cvt_pk_bf16_f32 v51, v40, v41
	v_cvt_pk_bf16_f32 v52, v42, v43
	v_cvt_pk_bf16_f32 v53, v44, v45
	global_store_dwordx2 v2, v[46:47], s[98:99]
	global_store_dwordx2 v2, v[48:49], s[98:99] offset:512
	global_store_dwordx2 v2, v[50:51], s[98:99] offset:1024
	global_store_dwordx2 v2, v[52:53], s[98:99] offset:1536
	s_mov_b32 s15, s41
	s_cmp_lt_i32 s15, 0x4100
	s_cbranch_scc1 .Lpm_a_loop

; DI float bflo(unsigned w) { return __uint_as_float(w << 16); }
; DI float bfhi(unsigned w) { return __uint_as_float(w & 0xffff0000u); }
; template <bool XI32>
; DI void phase_mod(const Frame& F, const void* xP, const void* xS, const float* g, const float* mods_l, int sidx, bool pool_out) {
;     ...
;     for (int row = F.gw; row < NT; row += F.NGW) {
;         const int seq = seq_of_row(row);
;         f32x4 v[4]; float ss = 0.f;
;         if constexpr (XI32) { const float* xr = (const float*)(row < NP ? xP : xS) + (size_t)row * DM + 4 * F.lane;
; #pragma unroll
;             for (int j = 0; j < 4; ++j) v[j] = *(const f32x4*)(xr + 256 * j);
;         } else { const bf16_t* xr = (const bf16_t*)xP + (size_t)row * DM + 4 * F.lane;
; #pragma unroll
;             for (int j = 0; j < 4; ++j) { const u32x2 q = *(const u32x2*)(xr + 256 * j); v[j] = (f32x4){bflo(q.x), bfhi(q.x), bflo(q.y), bfhi(q.y)}; } }
; #pragma unroll
;         for (int j = 0; j < 4; ++j) ss += (v[j][0] * v[j][0] + v[j][1] * v[j][1]) + (v[j][2] * v[j][2] + v[j][3] * v[j][3]);
;         const float rstd = 1.f / sqrtf(wave_sum(ss) * (1.f / DM) + EPS);
;         const float* sh = mods_l + (size_t)seq * MODW + sidx * DM; const float* sc = sh + DM;
;         const int pos = pos_of_row(row); const int tl = row < NP ? SEQ : DSEQ;
;         float* po = nullptr;
;         if (pool_out && pos >= tl - 15) po = row < NP ? F.out + O_PP + ((size_t)seq * 15 + (pos - (tl - 15))) * DM : F.out + O_PS + ((size_t)(seq - 2) * 15 + (pos - (tl - 15))) * DM;
;         f32x4 g4v[4], s4v[4], c4v[4];
; #pragma unroll
;         for (int j = 0; j < 4; ++j) { const int col = 4 * F.lane + 256 * j; g4v[j] = *(const f32x4*)(g + col); s4v[j] = *(const f32x4*)(sh + col); c4v[j] = *(const f32x4*)(sc + col); }
.LBB0_328:
	s_or_b64 exec, exec, s[20:21]
	v_readlane_b32 s0, v255, 32
	v_readlane_b32 s1, v255, 33
	s_and_b64 s[0:1], s[0:1], exec
	v_mov_b32_e32 v2, v220
	v_readlane_b32 s20, v255, 24
	s_waitcnt lgkmcnt(0)
	s_barrier
	s_cselect_b32 s24, 0, s20
	v_readfirstlane_b32 s0, v2
	s_ashr_i32 s0, s0, 6
	v_readlane_b32 s1, v253, 2
	s_add_i32 s26, s0, s1
	v_readlane_b32 s0, v254, 33
	v_readlane_b32 s2, v254, 34
	v_readlane_b32 s18, v254, 44
	v_mov_b32_e32 v1, s0
	ds_read_b64 v[4:5], v1
	v_mov_b32_e32 v1, s2
	s_mul_hi_u32 s21, s20, 0xc00
	s_mulk_i32 s20, 0xc00
	s_cmp_eq_u32 s24, 1
	s_waitcnt lgkmcnt(0)
	v_readfirstlane_b32 s0, v5
	v_readfirstlane_b32 s1, v4
	ds_read_b64 v[4:5], v1
	v_mov_b32_e32 v1, s18
	v_writelane_b32 v255, s20, 44
	s_cselect_b64 s[28:29], -1, 0
	s_cmp_lg_u32 s24, 1
	s_waitcnt lgkmcnt(0)
	v_readfirstlane_b32 s2, v5
	v_readfirstlane_b32 s15, v4
	ds_read_b64 v[4:5], v1
	v_writelane_b32 v255, s21, 45
	s_cselect_b64 s[20:21], -1, 0
	s_cmpk_gt_i32 s26, 0x40ff
	s_waitcnt lgkmcnt(0)
	v_readfirstlane_b32 s18, v5
	v_readfirstlane_b32 s19, v4
	s_cbranch_scc1 .LBB0_344
	v_and_b32_e32 v2, 63, v220
	v_mov_b32_e32 v5, 0x23110
	v_mov_b32_e32 v6, 0x23058
	ds_read_b64 v[8:9], v5
	ds_read_b64 v[10:11], v6
	v_lshlrev_b32_e32 v3, 4, v2
	v_lshlrev_b32_e32 v2, 3, v2
	v_add_u32_e32 v4, 0x1000, v3
	v_readlane_b32 s45, v255, 24
	v_readlane_b32 s25, v253, 2
	v_readfirstlane_b32 s15, v220
	s_lshr_b32 s15, s15, 6
	s_add_i32 s15, s15, s25
	s_waitcnt lgkmcnt(0)
	v_readfirstlane_b32 s42, v8
	v_readfirstlane_b32 s43, v9
	v_readfirstlane_b32 s78, v10
	v_readfirstlane_b32 s79, v11
	s_mul_i32 s25, s45, 0x3000
	s_add_i32 s25, s25, 4096
	s_add_u32 s78, s78, s25
	s_addc_u32 s79, s79, 0
	global_load_dwordx4 v[140:143], v3, s[78:79]
	global_load_dwordx4 v[144:147], v3, s[78:79] offset:1024
	global_load_dwordx4 v[148:151], v3, s[78:79] offset:2048
	global_load_dwordx4 v[152:155], v3, s[78:79] offset:3072
	s_mul_i32 s25, s45, 0x5a000
	s_add_i32 s25, s25, 1060864
	s_add_u32 s48, s42, s25
	s_addc_u32 s49, s43, 0
	s_lshl_b32 s25, s15, 11
	s_add_i32 s25, s25, 0xa400000
	s_add_u32 s92, s42, s25
	s_addc_u32 s93, s43, 0
	global_load_dwordx2 v[196:197], v2, s[92:93]
	global_load_dwordx2 v[198:199], v2, s[92:93] offset:512
	global_load_dwordx2 v[200:201], v2, s[92:93] offset:1024
	global_load_dwordx2 v[202:203], v2, s[92:93] offset:1536
; DI unsigned cvt_pk_bf16(float lo, float hi) { unsigned r; asm volatile("v_cvt_pk_bf16_f32 %0, %1, %2" : "=v"(r) : "v"(lo), "v"(hi)); return r; }
; DI float bflo(unsigned w) { return __uint_as_float(w << 16); }
; DI float bfhi(unsigned w) { return __uint_as_float(w & 0xffff0000u); }
; template <bool XI32>
; DI void phase_mod(const Frame& F, const void* xP, const void* xS, const float* g, const float* mods_l, int sidx, bool pool_out) {
;     ...
;     for (int row = F.gw; row < NT; row += F.NGW) {
;         const int seq = seq_of_row(row);
;         f32x4 v[4]; float ss = 0.f;
;         if constexpr (XI32) { const float* xr = (const float*)(row < NP ? xP : xS) + (size_t)row * DM + 4 * F.lane;
; #pragma unroll
;             for (int j = 0; j < 4; ++j) v[j] = *(const f32x4*)(xr + 256 * j);
;         } else { const bf16_t* xr = (const bf16_t*)xP + (size_t)row * DM + 4 * F.lane;
; #pragma unroll
;             for (int j = 0; j < 4; ++j) { const u32x2 q = *(const u32x2*)(xr + 256 * j); v[j] = (f32x4){bflo(q.x), bfhi(q.x), bflo(q.y), bfhi(q.y)}; } }
; #pragma unroll
;         for (int j = 0; j < 4; ++j) ss += (v[j][0] * v[j][0] + v[j][1] * v[j][1]) + (v[j][2] * v[j][2] + v[j][3] * v[j][3]);
;         const float rstd = 1.f / sqrtf(wave_sum(ss) * (1.f / DM) + EPS);
;         const float* sh = mods_l + (size_t)seq * MODW + sidx * DM; const float* sc = sh + DM;
;         const int pos = pos_of_row(row); const int tl = row < NP ? SEQ : DSEQ;
;         float* po = nullptr;
;         if (pool_out && pos >= tl - 15) po = row < NP ? F.out + O_PP + ((size_t)seq * 15 + (pos - (tl - 15))) * DM : F.out + O_PS + ((size_t)(seq - 2) * 15 + (pos - (tl - 15))) * DM;
;         f32x4 g4v[4], s4v[4], c4v[4];
; #pragma unroll
;         for (int j = 0; j < 4; ++j) { const int col = 4 * F.lane + 256 * j; g4v[j] = *(const f32x4*)(g + col); s4v[j] = *(const f32x4*)(sh + col); c4v[j] = *(const f32x4*)(sc + col); }
; #pragma unroll
;         for (int j = 0; j < 4; ++j) { const int col = 4 * F.lane + 256 * j;
;             const f32x4 g4 = g4v[j], s4 = s4v[j], c4 = c4v[j];
;             const f32x4 y = (v[j] * rstd) * g4 * (1.f + c4) + s4;
;             u32x2 w; w.x = cvt_pk_bf16(y[0], y[1]); w.y = cvt_pk_bf16(y[2], y[3]);
;             *(u32x2*)(U + (size_t)row * DM + col) = w;
;             if (po) *(f32x4*)(po + col) = y; }
;     }
.Lpm_b_loop:
	s_lshr_b32 s25, s15, 13
	s_sub_i32 s32, s15, 0x4000
	s_lshr_b32 s32, s32, 5
	s_add_i32 s32, s32, 2
	s_cmp_lt_i32 s15, 0x4000
	s_cselect_b32 s25, s25, s32
	s_mul_i32 s32, s25, 0x9000
	s_add_u32 s78, s48, s32
	s_addc_u32 s79, s49, 0
	global_load_dwordx4 v[156:159], v3, s[78:79]
	global_load_dwordx4 v[160:163], v3, s[78:79] offset:1024
	global_load_dwordx4 v[164:167], v3, s[78:79] offset:2048
	global_load_dwordx4 v[168:171], v3, s[78:79] offset:3072
	global_load_dwordx4 v[180:183], v4, s[78:79]
	global_load_dwordx4 v[184:187], v4, s[78:79] offset:1024
	global_load_dwordx4 v[188:191], v4, s[78:79] offset:2048
	global_load_dwordx4 v[192:195], v4, s[78:79] offset:3072
	s_lshl_b32 s32, s15, 11
	s_add_i32 s32, s32, 0xe500000
	s_add_u32 s98, s42, s32
	s_addc_u32 s99, s43, 0
	s_add_i32 s41, s15, s94
	s_lshl_b32 s32, s41, 11
	s_add_i32 s32, s32, 0xa400000
	s_add_u32 s92, s42, s32
	s_addc_u32 s93, s43, 0
	s_waitcnt vmcnt(8)
	v_lshlrev_b32_e32 v30, 16, v196
	v_and_b32_e32 v31, 0xffff0000, v196
	v_lshlrev_b32_e32 v32, 16, v197
	v_and_b32_e32 v33, 0xffff0000, v197
	v_lshlrev_b32_e32 v34, 16, v198
	v_and_b32_e32 v35, 0xffff0000, v198
	v_lshlrev_b32_e32 v36, 16, v199
	v_and_b32_e32 v37, 0xffff0000, v199
	v_lshlrev_b32_e32 v38, 16, v200
	v_and_b32_e32 v39, 0xffff0000, v200
	v_lshlrev_b32_e32 v40, 16, v201
	v_and_b32_e32 v41, 0xffff0000, v201
	v_lshlrev_b32_e32 v42, 16, v202
	v_and_b32_e32 v43, 0xffff0000, v202
	v_lshlrev_b32_e32 v44, 16, v203
	v_and_b32_e32 v45, 0xffff0000, v203
	global_load_dwordx2 v[196:197], v2, s[92:93]
	global_load_dwordx2 v[198:199], v2, s[92:93] offset:512
	global_load_dwordx2 v[200:201], v2, s[92:93] offset:1024
	global_load_dwordx2 v[202:203], v2, s[92:93] offset:1536
	v_mul_f32_e32 v5, v30, v30
	v_mul_f32_e32 v6, v31, v31
	v_mul_f32_e32 v7, v32, v32
	v_mul_f32_e32 v8, v33, v33
	v_fmac_f32_e32 v5, v34, v34
	v_fmac_f32_e32 v6, v35, v35
	v_fmac_f32_e32 v7, v36, v36
	v_fmac_f32_e32 v8, v37, v37
	v_fmac_f32_e32 v5, v38, v38
	v_fmac_f32_e32 v6, v39, v39
	v_fmac_f32_e32 v7, v40, v40
	v_fmac_f32_e32 v8, v41, v41
	v_fmac_f32_e32 v5, v42, v42
	v_fmac_f32_e32 v6, v43, v43
	v_fmac_f32_e32 v7, v44, v44
	v_fmac_f32_e32 v8, v45, v45
	v_add_f32_e32 v5, v5, v6
	v_add_f32_e32 v7, v7, v8
	v_add_f32_e32 v5, v5, v7
	s_nop 1
	v_add_f32_dpp v5, v5, v5 quad_perm:[1,0,3,2] row_mask:0xf bank_mask:0xf
	s_nop 1
	v_add_f32_dpp v5, v5, v5 quad_perm:[2,3,0,1] row_mask:0xf bank_mask:0xf
	s_nop 1
	v_add_f32_dpp v5, v5, v5 row_half_mirror row_mask:0xf bank_mask:0xf
	s_nop 1
	v_add_f32_dpp v5, v5, v5 row_mirror row_mask:0xf bank_mask:0xf
	s_nop 1
	v_readlane_b32 s25, v5, 0
	v_readlane_b32 s32, v5, 16
	v_readlane_b32 s66, v5, 32
	v_readlane_b32 s69, v5, 48
	v_mov_b32_e32 v7, 0x358637bd
	v_mov_b32_e32 v6, s25
	v_add_f32_e32 v6, s32, v6
	v_add_f32_e32 v6, s66, v6
	v_add_f32_e32 v6, s69, v6
	v_fmamk_f32 v6, v6, 0x3a800000, v7
	v_rsq_f32_e32 v58, v6
	s_waitcnt vmcnt(4)
	v_pk_add_f32 v[180:181], v[180:181], 1.0 op_sel_hi:[1,0]
	v_pk_add_f32 v[182:183], v[182:183], 1.0 op_sel_hi:[1,0]
	v_pk_add_f32 v[184:185], v[184:185], 1.0 op_sel_hi:[1,0]
	v_pk_add_f32 v[186:187], v[186:187], 1.0 op_sel_hi:[1,0]
	v_pk_add_f32 v[188:189], v[188:189], 1.0 op_sel_hi:[1,0]
	v_pk_add_f32 v[190:191], v[190:191], 1.0 op_sel_hi:[1,0]
	v_pk_add_f32 v[192:193], v[192:193], 1.0 op_sel_hi:[1,0]
	v_pk_add_f32 v[194:195], v[194:195], 1.0 op_sel_hi:[1,0]
	v_pk_mul_f32 v[30:31], v[58:59], v[30:31] op_sel_hi:[0,1]
	v_pk_mul_f32 v[32:33], v[58:59], v[32:33] op_sel_hi:[0,1]
	v_pk_mul_f32 v[34:35], v[58:59], v[34:35] op_sel_hi:[0,1]
	v_pk_mul_f32 v[36:37], v[58:59], v[36:37] op_sel_hi:[0,1]
	v_pk_mul_f32 v[38:39], v[58:59], v[38:39] op_sel_hi:[0,1]
	v_pk_mul_f32 v[40:41], v[58:59], v[40:41] op_sel_hi:[0,1]
	v_pk_mul_f32 v[42:43], v[58:59], v[42:43] op_sel_hi:[0,1]
	v_pk_mul_f32 v[44:45], v[58:59], v[44:45] op_sel_hi:[0,1]
	v_pk_mul_f32 v[30:31], v[30:31], v[140:141]
	v_pk_mul_f32 v[32:33], v[32:33], v[142:143]
	v_pk_mul_f32 v[34:35], v[34:35], v[144:145]
	v_pk_mul_f32 v[36:37], v[36:37], v[146:147]
	v_pk_mul_f32 v[38:39], v[38:39], v[148:149]
	v_pk_mul_f32 v[40:41], v[40:41], v[150:151]
	v_pk_mul_f32 v[42:43], v[42:43], v[152:153]
	v_pk_mul_f32 v[44:45], v[44:45], v[154:155]
	v_pk_fma_f32 v[30:31], v[30:31], v[180:181], v[156:157]
	v_pk_fma_f32 v[32:33], v[32:33], v[182:183], v[158:159]
	v_pk_fma_f32 v[34:35], v[34:35], v[184:185], v[160:161]
	v_pk_fma_f32 v[36:37], v[36:37], v[186:187], v[162:163]
	v_pk_fma_f32 v[38:39], v[38:39], v[188:189], v[164:165]
	v_pk_fma_f32 v[40:41], v[40:41], v[190:191], v[166:167]
	v_pk_fma_f32 v[42:43], v[42:43], v[192:193], v[168:169]
	v_pk_fma_f32 v[44:45], v[44:45], v[194:195], v[170:171]
	v_cvt_pk_bf16_f32 v46, v30, v31
	v_cvt_pk_bf16_f32 v47, v32, v33
	v_cvt_pk_bf16_f32 v48, v34, v35
	v_cvt_pk_bf16_f32 v49, v36, v37
	v_cvt_pk_bf16_f32 v50, v38, v39
	v_cvt_pk_bf16_f32 v51, v40, v41
	v_cvt_pk_bf16_f32 v52, v42, v43
	v_cvt_pk_bf16_f32 v53, v44, v45
	global_store_dwordx2 v2, v[46:47], s[98:99]
	global_store_dwordx2 v2, v[48:49], s[98:99] offset:512
	global_store_dwordx2 v2, v[50:51], s[98:99] offset:1024
	global_store_dwordx2 v2, v[52:53], s[98:99] offset:1536
	s_cmp_lg_u32 s24, 1
	s_cbranch_scc1 .Lpm_b_nopool
	s_cmp_lt_i32 s15, 0x4000
	s_cbranch_scc0 .Lpm_b_pool_s
	s_and_b32 s32, s15, 0x1fff
	s_cmp_lt_u32 s32, 0x1ff1
	s_cbranch_scc1 .Lpm_b_nopool
	s_lshr_b32 s66, s15, 13
	s_mul_i32 s66, s66, 15
	s_add_i32 s66, s66, s32
	s_sub_i32 s66, s66, 0x1ff1
	s_lshl_b32 s66, s66, 12
	s_add_i32 s66, s66, 0x4164000
	s_branch .Lpm_b_pool_st
.Lpm_b_pool_s:
	s_sub_i32 s32, s15, 0x4000
	s_and_b32 s66, s32, 31
	s_cmp_lt_u32 s66, 17
	s_cbranch_scc1 .Lpm_b_nopool
	s_lshr_b32 s32, s32, 5
	s_mul_i32 s32, s32, 15
	s_add_i32 s66, s66, s32
	s_sub_i32 s66, s66, 17
	s_lshl_b32 s66, s66, 12
	s_add_i32 s66, s66, 0x4182000
.Lpm_b_pool_st:
	v_mov_b32_e32 v9, 0x23108
	ds_read_b64 v[10:11], v9
	s_waitcnt lgkmcnt(0)
	v_readfirstlane_b32 s92, v10
	v_readfirstlane_b32 s93, v11
	s_add_u32 s92, s92, s66
	s_addc_u32 s93, s93, 0
	global_store_dwordx4 v3, v[30:33], s[92:93]
	global_store_dwordx4 v3, v[34:37], s[92:93] offset:1024
	global_store_dwordx4 v3, v[38:41], s[92:93] offset:2048
	global_store_dwordx4 v3, v[42:45], s[92:93] offset:3072
.Lpm_b_nopool:
	s_mov_b32 s15, s41
	s_cmp_lt_i32 s15, 0x4100
	s_cbranch_scc1 .Lpm_b_loop

; DI float bflo(unsigned w) { return __uint_as_float(w << 16); }
; DI float bfhi(unsigned w) { return __uint_as_float(w & 0xffff0000u); }
; template <bool XI32>
; DI void phase_mod(const Frame& F, const void* xP, const void* xS, const float* g, const float* mods_l, int sidx, bool pool_out) {
;     ...
;     for (int row = F.gw; row < NT; row += F.NGW) {
;         const int seq = seq_of_row(row);
;         f32x4 v[4]; float ss = 0.f;
;         if constexpr (XI32) { const float* xr = (const float*)(row < NP ? xP : xS) + (size_t)row * DM + 4 * F.lane;
; #pragma unroll
;             for (int j = 0; j < 4; ++j) v[j] = *(const f32x4*)(xr + 256 * j);
;         } else { const bf16_t* xr = (const bf16_t*)xP + (size_t)row * DM + 4 * F.lane;
; #pragma unroll
;             for (int j = 0; j < 4; ++j) { const u32x2 q = *(const u32x2*)(xr + 256 * j); v[j] = (f32x4){bflo(q.x), bfhi(q.x), bflo(q.y), bfhi(q.y)}; } }
; #pragma unroll
;         for (int j = 0; j < 4; ++j) ss += (v[j][0] * v[j][0] + v[j][1] * v[j][1]) + (v[j][2] * v[j][2] + v[j][3] * v[j][3]);
;         const float rstd = 1.f / sqrtf(wave_sum(ss) * (1.f / DM) + EPS);
;         const float* sh = mods_l + (size_t)seq * MODW + sidx * DM; const float* sc = sh + DM;
;         const int pos = pos_of_row(row); const int tl = row < NP ? SEQ : DSEQ;
;         float* po = nullptr;
;         if (pool_out && pos >= tl - 15) po = row < NP ? F.out + O_PP + ((size_t)seq * 15 + (pos - (tl - 15))) * DM : F.out + O_PS + ((size_t)(seq - 2) * 15 + (pos - (tl - 15))) * DM;
;         f32x4 g4v[4], s4v[4], c4v[4];
; #pragma unroll
;         for (int j = 0; j < 4; ++j) { const int col = 4 * F.lane + 256 * j; g4v[j] = *(const f32x4*)(g + col); s4v[j] = *(const f32x4*)(sh + col); c4v[j] = *(const f32x4*)(sc + col); }
.LBB0_2102:
	s_or_b64 exec, exec, s[0:1]
	v_mov_b32_e32 v2, v220
	s_waitcnt lgkmcnt(0)
	s_barrier
	v_readlane_b32 s1, v253, 2
	v_readfirstlane_b32 s0, v2
	s_ashr_i32 s0, s0, 6
	s_add_i32 s20, s0, s1
	v_readlane_b32 s0, v254, 33
	v_readlane_b32 s2, v254, 44
	s_cmpk_gt_i32 s20, 0x40ff
	v_mov_b32_e32 v1, s0
	v_readlane_b32 s0, v254, 34
	ds_read_b64 v[4:5], v1
	s_movk_i32 s84, 0x5000
	v_mov_b32_e32 v1, s0
	s_waitcnt lgkmcnt(0)
	ds_read_b64 v[4:5], v1
	v_mov_b32_e32 v1, s2
	s_waitcnt lgkmcnt(0)
	v_readfirstlane_b32 s0, v5
	v_readfirstlane_b32 s1, v4
	ds_read_b64 v[4:5], v1
	s_waitcnt lgkmcnt(0)
	v_readfirstlane_b32 s2, v5
	v_readfirstlane_b32 s15, v4
	s_cbranch_scc1 .LBB0_2105
	v_and_b32_e32 v2, 63, v220
	v_mov_b32_e32 v5, 0x23110
	v_mov_b32_e32 v6, 0x23058
	ds_read_b64 v[8:9], v5
	ds_read_b64 v[10:11], v6
	v_lshlrev_b32_e32 v3, 4, v2
	v_lshlrev_b32_e32 v2, 3, v2
	v_add_u32_e32 v4, 0x1000, v3
	v_readlane_b32 s45, v255, 24
	v_readlane_b32 s25, v253, 2
	v_readfirstlane_b32 s15, v220
	s_lshr_b32 s15, s15, 6
	s_add_i32 s15, s15, s25
	s_waitcnt lgkmcnt(0)
	v_readfirstlane_b32 s42, v8
	v_readfirstlane_b32 s43, v9
	v_readfirstlane_b32 s78, v10
	v_readfirstlane_b32 s79, v11
	s_mul_i32 s25, s45, 0x3000
	s_add_i32 s25, s25, 8192
	s_add_u32 s78, s78, s25
	s_addc_u32 s79, s79, 0
	global_load_dwordx4 v[140:143], v3, s[78:79]
	global_load_dwordx4 v[144:147], v3, s[78:79] offset:1024
	global_load_dwordx4 v[148:151], v3, s[78:79] offset:2048
	global_load_dwordx4 v[152:155], v3, s[78:79] offset:3072
	s_mul_i32 s25, s45, 0x5a000
	s_add_i32 s25, s25, 1073152
	s_add_u32 s48, s42, s25
	s_addc_u32 s49, s43, 0
	s_lshl_b32 s25, s15, 11
	s_add_i32 s25, s25, 0xa400000
	s_add_u32 s92, s42, s25
	s_addc_u32 s93, s43, 0
	global_load_dwordx2 v[196:197], v2, s[92:93]
	global_load_dwordx2 v[198:199], v2, s[92:93] offset:512
	global_load_dwordx2 v[200:201], v2, s[92:93] offset:1024
	global_load_dwordx2 v[202:203], v2, s[92:93] offset:1536
